# attention PV: V-fragment LDS reads issued right after the QK MFMAs (before softmax) into AGPR/VGPR quads freed by QK
# baseline (speedup 1.0000x reference)
; #define LAS __attribute__((address_space(3)))
; DI void phase_attn(const Params& p, int l, LAS char* lds) {
;     ...
; #pragma unroll
;             for (int r = 0; r < 16; ++r) { s0[r] = 0.f; s1[r] = 0.f; }
; #pragma unroll
;             for (int s = 0; s < 6; ++s) {
;                 const int pos = ((2 * s + hh) ^ ksw) << 4;
;                 const bf16x8 k0 = *(LAS bf16x8*)(st + qi * 192 + pos);
;                 const bf16x8 k1 = *(LAS bf16x8*)(st + (qi + 32) * 192 + pos);
;                 s0 = __builtin_amdgcn_mfma_f32_32x32x16_bf16(k0, qf[s], s0, 0, 0, 0);
;                 s1 = __builtin_amdgcn_mfma_f32_32x32x16_bf16(k1, qf[s], s1, 0, 0, 0);
;             }
;     ...
;                     const int c = 4 * tl + 2 * s2;
;                     const int p0 = ((c ^ vsw) << 4) + 8 * hh, p1 = (((c + 1) ^ vsw) << 4) + 8 * hh;
;                     const s16x4 a0 = *(LAS s16x4*)(vs + qi * 128 + p0), a1 = *(LAS s16x4*)(vs + qi * 128 + p1);
;                     const s16x4 b0 = *(LAS s16x4*)(vs + (qi + 32) * 128 + p0), b1 = *(LAS s16x4*)(vs + (qi + 32) * 128 + p1);
.LBB0_288:
	s_bitcmp1_b32 s4, 0
	s_cselect_b32 s34, 0x5000, 0
	s_cbranch_scc1 .Lqk_s1
	ds_read_b128 v[34:37], v188 offset:0
	ds_read_b128 v[50:53], v188 offset:6144
	ds_read_b128 v[184:187], v189 offset:0
	ds_read_b128 a[0:3], v189 offset:6144
	ds_read_b128 v[204:207], v190 offset:0
	ds_read_b128 a[4:7], v190 offset:6144
	ds_read_b128 v[220:223], v191 offset:0
	ds_read_b128 a[8:11], v191 offset:6144
	ds_read_b128 v[224:227], v192 offset:0
	ds_read_b128 a[12:15], v192 offset:6144
	ds_read_b128 a[16:19], v193 offset:0
	ds_read_b128 a[20:23], v193 offset:6144
	s_add_i32 s4, s23, 63
	v_cmp_gt_i32_e32 vcc, s4, v123
	s_waitcnt lgkmcnt(10)
	v_mfma_f32_32x32x16_bf16 v[34:49], v[34:37], v[66:69], 0
	v_mfma_f32_32x32x16_bf16 v[50:65], v[50:53], v[66:69], 0
	s_waitcnt lgkmcnt(8)
	v_mfma_f32_32x32x16_bf16 v[34:49], v[184:187], v[70:73], v[34:49]
	v_mfma_f32_32x32x16_bf16 v[50:65], a[0:3], v[70:73], v[50:65]
	s_waitcnt lgkmcnt(6)
	v_mfma_f32_32x32x16_bf16 v[34:49], v[204:207], v[74:77], v[34:49]
	v_mfma_f32_32x32x16_bf16 v[50:65], a[4:7], v[74:77], v[50:65]
	s_waitcnt lgkmcnt(4)
	v_mfma_f32_32x32x16_bf16 v[34:49], v[220:223], v[78:81], v[34:49]
	v_mfma_f32_32x32x16_bf16 v[50:65], a[8:11], v[78:81], v[50:65]
	s_waitcnt lgkmcnt(2)
	v_mfma_f32_32x32x16_bf16 v[34:49], v[224:227], v[82:85], v[34:49]
	v_mfma_f32_32x32x16_bf16 v[50:65], a[12:15], v[82:85], v[50:65]
	s_waitcnt lgkmcnt(0)
	v_mfma_f32_32x32x16_bf16 v[34:49], a[16:19], v[86:89], v[34:49]
	v_mfma_f32_32x32x16_bf16 v[50:65], a[20:23], v[86:89], v[50:65]
	ds_read_b64 a[0:1], v194 offset:12288
	ds_read_b64 a[4:5], v194 offset:16384
	ds_read_b64 a[2:3], v195 offset:12288
	ds_read_b64 a[6:7], v195 offset:16384
	ds_read_b64 a[8:9], v196 offset:12288
	ds_read_b64 a[12:13], v196 offset:16384
	ds_read_b64 a[10:11], v197 offset:12288
	ds_read_b64 a[14:15], v197 offset:16384
	ds_read_b64 a[16:17], v198 offset:12288
	ds_read_b64 a[20:21], v198 offset:16384
	ds_read_b64 a[18:19], v199 offset:12288
	ds_read_b64 a[22:23], v199 offset:16384
	ds_read_b64 v[220:221], v200 offset:12288
	ds_read_b64 v[224:225], v200 offset:16384
	ds_read_b64 v[222:223], v201 offset:12288
	ds_read_b64 v[226:227], v201 offset:16384
	s_nop 1
	s_branch .Lqk_done
.Lqk_s1:
	ds_read_b128 v[34:37], v188 offset:20480
	ds_read_b128 v[50:53], v188 offset:26624
	ds_read_b128 v[184:187], v189 offset:20480
	ds_read_b128 a[0:3], v189 offset:26624
	ds_read_b128 v[204:207], v190 offset:20480
	ds_read_b128 a[4:7], v190 offset:26624
	ds_read_b128 v[220:223], v191 offset:20480
	ds_read_b128 a[8:11], v191 offset:26624
	ds_read_b128 v[224:227], v192 offset:20480
	ds_read_b128 a[12:15], v192 offset:26624
	ds_read_b128 a[16:19], v193 offset:20480
	ds_read_b128 a[20:23], v193 offset:26624
	s_add_i32 s4, s23, 63
	v_cmp_gt_i32_e32 vcc, s4, v123
	s_waitcnt lgkmcnt(10)
	v_mfma_f32_32x32x16_bf16 v[34:49], v[34:37], v[66:69], 0
	v_mfma_f32_32x32x16_bf16 v[50:65], v[50:53], v[66:69], 0
	s_waitcnt lgkmcnt(8)
	v_mfma_f32_32x32x16_bf16 v[34:49], v[184:187], v[70:73], v[34:49]
	v_mfma_f32_32x32x16_bf16 v[50:65], a[0:3], v[70:73], v[50:65]
	s_waitcnt lgkmcnt(6)
	v_mfma_f32_32x32x16_bf16 v[34:49], v[204:207], v[74:77], v[34:49]
	v_mfma_f32_32x32x16_bf16 v[50:65], a[4:7], v[74:77], v[50:65]
	s_waitcnt lgkmcnt(4)
	v_mfma_f32_32x32x16_bf16 v[34:49], v[220:223], v[78:81], v[34:49]
	v_mfma_f32_32x32x16_bf16 v[50:65], a[8:11], v[78:81], v[50:65]
	s_waitcnt lgkmcnt(2)
	v_mfma_f32_32x32x16_bf16 v[34:49], v[224:227], v[82:85], v[34:49]
	v_mfma_f32_32x32x16_bf16 v[50:65], a[12:15], v[82:85], v[50:65]
	s_waitcnt lgkmcnt(0)
	v_mfma_f32_32x32x16_bf16 v[34:49], a[16:19], v[86:89], v[34:49]
	v_mfma_f32_32x32x16_bf16 v[50:65], a[20:23], v[86:89], v[50:65]
	ds_read_b64 a[0:1], v194 offset:32768
	ds_read_b64 a[4:5], v194 offset:36864
	ds_read_b64 a[2:3], v195 offset:32768
	ds_read_b64 a[6:7], v195 offset:36864
	ds_read_b64 a[8:9], v196 offset:32768
	ds_read_b64 a[12:13], v196 offset:36864
	ds_read_b64 a[10:11], v197 offset:32768
	ds_read_b64 a[14:15], v197 offset:36864
	ds_read_b64 a[16:17], v198 offset:32768
	ds_read_b64 a[20:21], v198 offset:36864
	ds_read_b64 a[18:19], v199 offset:32768
	ds_read_b64 a[22:23], v199 offset:36864
	ds_read_b64 v[220:221], v200 offset:32768
	ds_read_b64 v[224:225], v200 offset:36864
	ds_read_b64 v[222:223], v201 offset:32768
	ds_read_b64 v[226:227], v201 offset:36864
	s_nop 1

; #define LAS __attribute__((address_space(3)))
; DI unsigned pk2(float lo, float hi) { f32x2 v = {lo, hi}; bf2_t r = __builtin_convertvector(v, bf2_t); return __builtin_bit_cast(unsigned, r); }
; DI void phase_attn(const Params& p, int l, LAS char* lds) {
;     ...
;             float ps = 0.f;
; #pragma unroll
;             for (int r = 0; r < 16; ++r) { s0[r] = __builtin_amdgcn_exp2f(s0[r] - m_new); s1[r] = __builtin_amdgcn_exp2f(s1[r] - m_new); ps += s0[r] + s1[r]; }
;             l_run += ps;
;             bf16x8 pf[2][2];
; #pragma unroll
;             for (int s2 = 0; s2 < 2; ++s2) {
;                 u32x4 a, c2;
; #pragma unroll
;                 for (int e = 0; e < 4; ++e) { a[e] = pk2(s0[8 * s2 + 2 * e], s0[8 * s2 + 2 * e + 1]); c2[e] = pk2(s1[8 * s2 + 2 * e], s1[8 * s2 + 2 * e + 1]); }
;                 pf[0][s2] = __builtin_bit_cast(bf16x8, a); pf[1][s2] = __builtin_bit_cast(bf16x8, c2);
;             }
;             LAS char* vs = st + 12288;
;             __builtin_amdgcn_s_setprio(0);
; #pragma unroll
;             for (int tl = 0; tl < 2; ++tl)
; #pragma unroll
;                 for (int s2 = 0; s2 < 2; ++s2) {
;                     const int c = 4 * tl + 2 * s2;
;                     const int p0 = ((c ^ vsw) << 4) + 8 * hh, p1 = (((c + 1) ^ vsw) << 4) + 8 * hh;
;                     const s16x4 a0 = *(LAS s16x4*)(vs + qi * 128 + p0), a1 = *(LAS s16x4*)(vs + qi * 128 + p1);
;                     const s16x4 b0 = *(LAS s16x4*)(vs + (qi + 32) * 128 + p0), b1 = *(LAS s16x4*)(vs + (qi + 32) * 128 + p1);
;                     const bf16x8 v0 = __builtin_shufflevector(a0, a1, 0, 1, 2, 3, 4, 5, 6, 7);
;                     const bf16x8 v1 = __builtin_shufflevector(b0, b1, 0, 1, 2, 3, 4, 5, 6, 7);
;                     o0 = __builtin_amdgcn_mfma_f32_32x32x16_bf16(v0, pf[tl][s2], o0, 0, 0, 0);
;                     o1 = __builtin_amdgcn_mfma_f32_32x32x16_bf16(v1, pf[tl][s2], o1, 0, 0, 0);
;                 }
.LBB0_292:
	v_sub_f32_e32 v34, v34, v182
	v_sub_f32_e32 v35, v35, v182
	v_sub_f32_e32 v36, v36, v182
	v_sub_f32_e32 v37, v37, v182
	v_sub_f32_e32 v38, v38, v182
	v_sub_f32_e32 v39, v39, v182
	v_sub_f32_e32 v40, v40, v182
	v_sub_f32_e32 v41, v41, v182
	v_sub_f32_e32 v42, v42, v182
	v_sub_f32_e32 v43, v43, v182
	v_sub_f32_e32 v44, v44, v182
	v_sub_f32_e32 v45, v45, v182
	v_sub_f32_e32 v46, v46, v182
	v_sub_f32_e32 v47, v47, v182
	v_sub_f32_e32 v48, v48, v182
	v_sub_f32_e32 v49, v49, v182
	v_sub_f32_e32 v50, v50, v182
	v_sub_f32_e32 v51, v51, v182
	v_sub_f32_e32 v52, v52, v182
	v_sub_f32_e32 v53, v53, v182
	v_sub_f32_e32 v54, v54, v182
	v_sub_f32_e32 v55, v55, v182
	v_sub_f32_e32 v56, v56, v182
	v_sub_f32_e32 v57, v57, v182
	v_sub_f32_e32 v58, v58, v182
	v_sub_f32_e32 v59, v59, v182
	v_sub_f32_e32 v60, v60, v182
	v_sub_f32_e32 v61, v61, v182
	v_sub_f32_e32 v62, v62, v182
	v_sub_f32_e32 v63, v63, v182
	v_sub_f32_e32 v64, v64, v182
	v_sub_f32_e32 v65, v65, v182
	v_exp_f32_e32 v34, v34
	v_exp_f32_e32 v35, v35
	v_exp_f32_e32 v36, v36
	v_exp_f32_e32 v37, v37
	v_exp_f32_e32 v38, v38
	v_exp_f32_e32 v39, v39
	v_exp_f32_e32 v40, v40
	v_exp_f32_e32 v41, v41
	v_exp_f32_e32 v42, v42
	v_exp_f32_e32 v43, v43
	v_exp_f32_e32 v44, v44
	v_exp_f32_e32 v45, v45
	v_exp_f32_e32 v46, v46
	v_exp_f32_e32 v47, v47
	v_exp_f32_e32 v48, v48
	v_exp_f32_e32 v49, v49
	v_exp_f32_e32 v50, v50
	v_exp_f32_e32 v51, v51
	v_exp_f32_e32 v52, v52
	v_exp_f32_e32 v53, v53
	v_exp_f32_e32 v54, v54
	v_exp_f32_e32 v55, v55
	v_exp_f32_e32 v56, v56
	v_exp_f32_e32 v57, v57
	v_exp_f32_e32 v58, v58
	v_exp_f32_e32 v59, v59
	v_exp_f32_e32 v60, v60
	v_exp_f32_e32 v61, v61
	v_exp_f32_e32 v62, v62
	v_exp_f32_e32 v63, v63
	v_exp_f32_e32 v64, v64
	v_exp_f32_e32 v65, v65
	v_add_f32_e32 v184, v34, v35
	v_add_f32_e32 v185, v50, v51
	v_add_f32_e32 v186, v36, v37
	v_add_f32_e32 v187, v52, v53
	v_add_f32_e32 v184, v184, v38
	v_add_f32_e32 v185, v185, v54
	v_add_f32_e32 v186, v186, v39
	v_add_f32_e32 v187, v187, v55
	v_add_f32_e32 v184, v184, v40
	v_add_f32_e32 v185, v185, v56
	v_add_f32_e32 v186, v186, v41
	v_add_f32_e32 v187, v187, v57
	v_add_f32_e32 v184, v184, v42
	v_add_f32_e32 v185, v185, v58
	v_add_f32_e32 v186, v186, v43
	v_add_f32_e32 v187, v187, v59
	v_add_f32_e32 v184, v184, v44
	v_add_f32_e32 v185, v185, v60
	v_add_f32_e32 v186, v186, v45
	v_add_f32_e32 v187, v187, v61
	v_add_f32_e32 v184, v184, v46
	v_add_f32_e32 v185, v185, v62
	v_add_f32_e32 v186, v186, v47
	v_add_f32_e32 v187, v187, v63
	v_add_f32_e32 v184, v184, v48
	v_add_f32_e32 v185, v185, v64
	v_add_f32_e32 v186, v186, v49
	v_add_f32_e32 v187, v187, v65
	v_add_f32_e32 v184, v184, v186
	v_add_f32_e32 v185, v185, v187
	v_add_f32_e32 v1, v184, v185
	v_cvt_pk_bf16_f32 v34, v34, v35
	v_cvt_pk_bf16_f32 v35, v36, v37
	v_cvt_pk_bf16_f32 v36, v38, v39
	v_cvt_pk_bf16_f32 v37, v40, v41
	v_cvt_pk_bf16_f32 v38, v42, v43
	v_cvt_pk_bf16_f32 v39, v44, v45
	v_cvt_pk_bf16_f32 v40, v46, v47
	v_cvt_pk_bf16_f32 v41, v48, v49
	v_cvt_pk_bf16_f32 v42, v50, v51
	v_cvt_pk_bf16_f32 v43, v52, v53
	v_cvt_pk_bf16_f32 v44, v54, v55
	v_cvt_pk_bf16_f32 v45, v56, v57
	v_cvt_pk_bf16_f32 v46, v58, v59
	v_cvt_pk_bf16_f32 v47, v60, v61
	v_cvt_pk_bf16_f32 v48, v62, v63
	v_cvt_pk_bf16_f32 v49, v64, v65
	v_add_f32_e32 v181, v181, v1
	s_setprio 0
	s_waitcnt lgkmcnt(12)
	v_mfma_f32_32x32x16_bf16 v[18:33], a[0:3], v[34:37], v[18:33]
	v_mfma_f32_32x32x16_bf16 v[2:17], a[4:7], v[34:37], v[2:17]
	s_waitcnt lgkmcnt(8)
	v_mfma_f32_32x32x16_bf16 v[18:33], a[8:11], v[38:41], v[18:33]
	v_mfma_f32_32x32x16_bf16 v[2:17], a[12:15], v[38:41], v[2:17]
	s_waitcnt lgkmcnt(4)
	v_mfma_f32_32x32x16_bf16 v[18:33], a[16:19], v[42:45], v[18:33]
	v_mfma_f32_32x32x16_bf16 v[2:17], a[20:23], v[42:45], v[2:17]
	s_waitcnt lgkmcnt(0)
	v_mfma_f32_32x32x16_bf16 v[18:33], v[220:223], v[46:49], v[18:33]
	v_mfma_f32_32x32x16_bf16 v[2:17], v[224:227], v[46:49], v[2:17]
	s_or_b64 exec, exec, s[48:49]
	s_add_i32 s23, s23, 64
	s_cmp_eq_u32 s1, s33
	s_cbranch_scc1 .LBB0_294
